# branch-merge GEMM final epilogue: all 16 gate loads in flight with counted waits
# speedup vs baseline: 1.0204x; 1.0022x over previous
; #define LAS __attribute__((address_space(3)))
; __device__ __forceinline__ unsigned cvt_pk_bf16(float lo, float hi) { unsigned r; asm volatile("v_cvt_pk_bf16_f32 %0, %1, %2" : "=v"(r) : "v"(lo), "v"(hi)); return r; }
; __device__ __forceinline__ float bflo(unsigned w) { return __uint_as_float(w << 16); }
; __device__ __forceinline__ float bfhi(unsigned w) { return __uint_as_float(w & 0xffff0000u); }
;     __device__ __forceinline__ void operator()(f32x4 (&acc)[2][2][4][2], const pg8::Unit& u, int wr, int wc, int fr, int fq, LAS unsigned char*) const {
;         const int row0 = u.pm * 256 + wr * 64 + fr, col0 = u.pn * 256 + wc * 32 + 8 * fq;
; #pragma unroll
;         for (int ai = 0; ai < 2; ++ai)
; #pragma unroll
;             for (int m = 0; m < 4; ++m) {
;                 const int row = row0 + ai * 128 + m * 16;
; #pragma unroll
;                 for (int bj = 0; bj < 2; ++bj) {
;                     const int col = col0 + bj * 128;
;                     const u32x4 gw = *(const u32x4*)(gates + (size_t)row * 3072 + 2048 + col);
;                     const f32x4 v0 = acc[ai][bj][m][0], v1 = acc[ai][bj][m][1];
;                     u32x4 w; w.x = cvt_pk_bf16(v0[0] * bflo(gw.x), v0[1] * bfhi(gw.x)); w.y = cvt_pk_bf16(v0[2] * bflo(gw.y), v0[3] * bfhi(gw.y));
;                     w.z = cvt_pk_bf16(v1[0] * bflo(gw.z), v1[1] * bfhi(gw.z)); w.w = cvt_pk_bf16(v1[2] * bflo(gw.w), v1[3] * bfhi(gw.w));
;                     *(u32x4*)(Y + (size_t)row * DM + col) = w;
;                 }
;             }
;     }
.LBB0_114:
	v_add_u32_e32 v162, s23, v166
	v_or_b32_e32 v163, s84, v168
	v_mul_u32_u24_e32 v246, 0x1800, v162
	v_lshl_add_u32 v246, v163, 1, v246
	v_add_u32_e32 v246, 0x1000, v246
	v_lshlrev_b32_e32 v247, 11, v162
	v_lshl_add_u32 v247, v163, 1, v247
	global_load_dwordx4 v[198:201], v246, s[12:13]
	global_load_dwordx4 v[202:205], v246, s[12:13] offset:256
	v_add_u32_e32 v248, 0x18000, v246
	global_load_dwordx4 v[206:209], v248, s[12:13]
	global_load_dwordx4 v[210:213], v248, s[12:13] offset:256
	v_add_u32_e32 v248, 0x30000, v246
	global_load_dwordx4 v[214:217], v248, s[12:13]
	global_load_dwordx4 v[218:221], v248, s[12:13] offset:256
	v_add_u32_e32 v248, 0x48000, v246
	global_load_dwordx4 v[222:225], v248, s[12:13]
	global_load_dwordx4 v[226:229], v248, s[12:13] offset:256
	v_add_u32_e32 v248, 0xc0000, v246
	global_load_dwordx4 v[230:233], v248, s[12:13]
	global_load_dwordx4 v[234:237], v248, s[12:13] offset:256
	v_add_u32_e32 v248, 0xd8000, v246
	global_load_dwordx4 v[238:241], v248, s[12:13]
	global_load_dwordx4 v[130:133], v248, s[12:13] offset:256
	v_add_u32_e32 v248, 0xf0000, v246
	global_load_dwordx4 v[134:137], v248, s[12:13]
	global_load_dwordx4 v[170:173], v248, s[12:13] offset:256
	v_add_u32_e32 v248, 0x108000, v246
	global_load_dwordx4 v[174:177], v248, s[12:13]
	global_load_dwordx4 v[178:181], v248, s[12:13] offset:256
	s_waitcnt vmcnt(15)
	v_lshlrev_b32_e32 v250, 16, v198
	v_and_b32_e32 v251, 0xffff0000, v198
	v_lshlrev_b32_e32 v252, 16, v199
	v_and_b32_e32 v253, 0xffff0000, v199
	v_mul_f32_e32 v126, v126, v250
	v_mul_f32_e32 v127, v127, v251
	v_mul_f32_e32 v128, v128, v252
	v_mul_f32_e32 v129, v129, v253
	v_lshlrev_b32_e32 v250, 16, v200
	v_and_b32_e32 v251, 0xffff0000, v200
	v_lshlrev_b32_e32 v252, 16, v201
	v_and_b32_e32 v253, 0xffff0000, v201
	v_mul_f32_e32 v122, v122, v250
	v_mul_f32_e32 v123, v123, v251
	v_mul_f32_e32 v124, v124, v252
	v_mul_f32_e32 v125, v125, v253
	v_cvt_pk_bf16_f32 v198, v126, v127
	v_cvt_pk_bf16_f32 v199, v128, v129
	v_cvt_pk_bf16_f32 v200, v122, v123
	v_cvt_pk_bf16_f32 v201, v124, v125
	global_store_dwordx4 v247, v[198:201], s[14:15]
	s_waitcnt vmcnt(15)
	v_lshlrev_b32_e32 v250, 16, v202
	v_and_b32_e32 v251, 0xffff0000, v202
	v_lshlrev_b32_e32 v252, 16, v203
	v_and_b32_e32 v253, 0xffff0000, v203
	v_mul_f32_e32 v118, v118, v250
	v_mul_f32_e32 v119, v119, v251
	v_mul_f32_e32 v120, v120, v252
	v_mul_f32_e32 v121, v121, v253
	v_lshlrev_b32_e32 v250, 16, v204
	v_and_b32_e32 v251, 0xffff0000, v204
	v_lshlrev_b32_e32 v252, 16, v205
	v_and_b32_e32 v253, 0xffff0000, v205
	v_mul_f32_e32 v114, v114, v250
	v_mul_f32_e32 v115, v115, v251
	v_mul_f32_e32 v116, v116, v252
	v_mul_f32_e32 v117, v117, v253
	v_cvt_pk_bf16_f32 v202, v118, v119
	v_cvt_pk_bf16_f32 v203, v120, v121
	v_cvt_pk_bf16_f32 v204, v114, v115
	v_cvt_pk_bf16_f32 v205, v116, v117
	global_store_dwordx4 v247, v[202:205], s[14:15] offset:256
	v_add_u32_e32 v249, 0x8000, v247
	s_waitcnt vmcnt(15)
	v_lshlrev_b32_e32 v250, 16, v206
	v_and_b32_e32 v251, 0xffff0000, v206
	v_lshlrev_b32_e32 v252, 16, v207
	v_and_b32_e32 v253, 0xffff0000, v207
	v_mul_f32_e32 v110, v110, v250
	v_mul_f32_e32 v111, v111, v251
	v_mul_f32_e32 v112, v112, v252
	v_mul_f32_e32 v113, v113, v253
	v_lshlrev_b32_e32 v250, 16, v208
	v_and_b32_e32 v251, 0xffff0000, v208
	v_lshlrev_b32_e32 v252, 16, v209
	v_and_b32_e32 v253, 0xffff0000, v209
	v_mul_f32_e32 v106, v106, v250
	v_mul_f32_e32 v107, v107, v251
	v_mul_f32_e32 v108, v108, v252
	v_mul_f32_e32 v109, v109, v253
	v_cvt_pk_bf16_f32 v206, v110, v111
	v_cvt_pk_bf16_f32 v207, v112, v113
	v_cvt_pk_bf16_f32 v208, v106, v107
	v_cvt_pk_bf16_f32 v209, v108, v109
	global_store_dwordx4 v249, v[206:209], s[14:15]
	s_waitcnt vmcnt(15)
	v_lshlrev_b32_e32 v250, 16, v210
	v_and_b32_e32 v251, 0xffff0000, v210
	v_lshlrev_b32_e32 v252, 16, v211
	v_and_b32_e32 v253, 0xffff0000, v211
	v_mul_f32_e32 v102, v102, v250
	v_mul_f32_e32 v103, v103, v251
	v_mul_f32_e32 v104, v104, v252
	v_mul_f32_e32 v105, v105, v253
	v_lshlrev_b32_e32 v250, 16, v212
	v_and_b32_e32 v251, 0xffff0000, v212
	v_lshlrev_b32_e32 v252, 16, v213
	v_and_b32_e32 v253, 0xffff0000, v213
	v_mul_f32_e32 v98, v98, v250
	v_mul_f32_e32 v99, v99, v251
	v_mul_f32_e32 v100, v100, v252
	v_mul_f32_e32 v101, v101, v253
	v_cvt_pk_bf16_f32 v210, v102, v103
	v_cvt_pk_bf16_f32 v211, v104, v105
	v_cvt_pk_bf16_f32 v212, v98, v99
	v_cvt_pk_bf16_f32 v213, v100, v101
	global_store_dwordx4 v249, v[210:213], s[14:15] offset:256
	v_add_u32_e32 v249, 0x10000, v247
	s_waitcnt vmcnt(15)
	v_lshlrev_b32_e32 v250, 16, v214
	v_and_b32_e32 v251, 0xffff0000, v214
	v_lshlrev_b32_e32 v252, 16, v215
	v_and_b32_e32 v253, 0xffff0000, v215
	v_mul_f32_e32 v94, v94, v250
	v_mul_f32_e32 v95, v95, v251
	v_mul_f32_e32 v96, v96, v252
	v_mul_f32_e32 v97, v97, v253
	v_lshlrev_b32_e32 v250, 16, v216
	v_and_b32_e32 v251, 0xffff0000, v216
	v_lshlrev_b32_e32 v252, 16, v217
	v_and_b32_e32 v253, 0xffff0000, v217
	v_mul_f32_e32 v90, v90, v250
	v_mul_f32_e32 v91, v91, v251
	v_mul_f32_e32 v92, v92, v252
	v_mul_f32_e32 v93, v93, v253
	v_cvt_pk_bf16_f32 v214, v94, v95
	v_cvt_pk_bf16_f32 v215, v96, v97
	v_cvt_pk_bf16_f32 v216, v90, v91
	v_cvt_pk_bf16_f32 v217, v92, v93
	global_store_dwordx4 v249, v[214:217], s[14:15]
	s_waitcnt vmcnt(15)
	v_lshlrev_b32_e32 v250, 16, v218
	v_and_b32_e32 v251, 0xffff0000, v218
	v_lshlrev_b32_e32 v252, 16, v219
	v_and_b32_e32 v253, 0xffff0000, v219
	v_mul_f32_e32 v86, v86, v250
	v_mul_f32_e32 v87, v87, v251
	v_mul_f32_e32 v88, v88, v252
	v_mul_f32_e32 v89, v89, v253
	v_lshlrev_b32_e32 v250, 16, v220
	v_and_b32_e32 v251, 0xffff0000, v220
	v_lshlrev_b32_e32 v252, 16, v221
	v_and_b32_e32 v253, 0xffff0000, v221
	v_mul_f32_e32 v82, v82, v250
	v_mul_f32_e32 v83, v83, v251
	v_mul_f32_e32 v84, v84, v252
	v_mul_f32_e32 v85, v85, v253
	v_cvt_pk_bf16_f32 v218, v86, v87
	v_cvt_pk_bf16_f32 v219, v88, v89
	v_cvt_pk_bf16_f32 v220, v82, v83
	v_cvt_pk_bf16_f32 v221, v84, v85
	global_store_dwordx4 v249, v[218:221], s[14:15] offset:256
	v_add_u32_e32 v249, 0x18000, v247
	s_waitcnt vmcnt(15)
; __device__ __forceinline__ unsigned cvt_pk_bf16(float lo, float hi) { unsigned r; asm volatile("v_cvt_pk_bf16_f32 %0, %1, %2" : "=v"(r) : "v"(lo), "v"(hi)); return r; }
; __device__ __forceinline__ float bflo(unsigned w) { return __uint_as_float(w << 16); }
; __device__ __forceinline__ float bfhi(unsigned w) { return __uint_as_float(w & 0xffff0000u); }
;     __device__ __forceinline__ void operator()(f32x4 (&acc)[2][2][4][2], const pg8::Unit& u, int wr, int wc, int fr, int fq, LAS unsigned char*) const {
;     ...
;             for (int m = 0; m < 4; ++m) {
;                 const int row = row0 + ai * 128 + m * 16;
; #pragma unroll
;                 for (int bj = 0; bj < 2; ++bj) {
;                     const int col = col0 + bj * 128;
;                     const u32x4 gw = *(const u32x4*)(gates + (size_t)row * 3072 + 2048 + col);
;                     const f32x4 v0 = acc[ai][bj][m][0], v1 = acc[ai][bj][m][1];
;                     u32x4 w; w.x = cvt_pk_bf16(v0[0] * bflo(gw.x), v0[1] * bfhi(gw.x)); w.y = cvt_pk_bf16(v0[2] * bflo(gw.y), v0[3] * bfhi(gw.y));
;                     w.z = cvt_pk_bf16(v1[0] * bflo(gw.z), v1[1] * bfhi(gw.z)); w.w = cvt_pk_bf16(v1[2] * bflo(gw.w), v1[3] * bfhi(gw.w));
;                     *(u32x4*)(Y + (size_t)row * DM + col) = w;
;                 }
;             }
	v_lshlrev_b32_e32 v250, 16, v222
	v_and_b32_e32 v251, 0xffff0000, v222
	v_lshlrev_b32_e32 v252, 16, v223
	v_and_b32_e32 v253, 0xffff0000, v223
	v_mul_f32_e32 v78, v78, v250
	v_mul_f32_e32 v79, v79, v251
	v_mul_f32_e32 v80, v80, v252
	v_mul_f32_e32 v81, v81, v253
	v_lshlrev_b32_e32 v250, 16, v224
	v_and_b32_e32 v251, 0xffff0000, v224
	v_lshlrev_b32_e32 v252, 16, v225
	v_and_b32_e32 v253, 0xffff0000, v225
	v_mul_f32_e32 v74, v74, v250
	v_mul_f32_e32 v75, v75, v251
	v_mul_f32_e32 v76, v76, v252
	v_mul_f32_e32 v77, v77, v253
	v_cvt_pk_bf16_f32 v222, v78, v79
	v_cvt_pk_bf16_f32 v223, v80, v81
	v_cvt_pk_bf16_f32 v224, v74, v75
	v_cvt_pk_bf16_f32 v225, v76, v77
	global_store_dwordx4 v249, v[222:225], s[14:15]
	s_waitcnt vmcnt(15)
	v_lshlrev_b32_e32 v250, 16, v226
	v_and_b32_e32 v251, 0xffff0000, v226
	v_lshlrev_b32_e32 v252, 16, v227
	v_and_b32_e32 v253, 0xffff0000, v227
	v_mul_f32_e32 v70, v70, v250
	v_mul_f32_e32 v71, v71, v251
	v_mul_f32_e32 v72, v72, v252
	v_mul_f32_e32 v73, v73, v253
	v_lshlrev_b32_e32 v250, 16, v228
	v_and_b32_e32 v251, 0xffff0000, v228
	v_lshlrev_b32_e32 v252, 16, v229
	v_and_b32_e32 v253, 0xffff0000, v229
	v_mul_f32_e32 v66, v66, v250
	v_mul_f32_e32 v67, v67, v251
	v_mul_f32_e32 v68, v68, v252
	v_mul_f32_e32 v69, v69, v253
	v_cvt_pk_bf16_f32 v226, v70, v71
	v_cvt_pk_bf16_f32 v227, v72, v73
	v_cvt_pk_bf16_f32 v228, v66, v67
	v_cvt_pk_bf16_f32 v229, v68, v69
	global_store_dwordx4 v249, v[226:229], s[14:15] offset:256
	v_add_u32_e32 v249, 0x40000, v247
	s_waitcnt vmcnt(15)
	v_lshlrev_b32_e32 v250, 16, v230
	v_and_b32_e32 v251, 0xffff0000, v230
	v_lshlrev_b32_e32 v252, 16, v231
	v_and_b32_e32 v253, 0xffff0000, v231
	v_mul_f32_e32 v62, v62, v250
	v_mul_f32_e32 v63, v63, v251
	v_mul_f32_e32 v64, v64, v252
	v_mul_f32_e32 v65, v65, v253
	v_lshlrev_b32_e32 v250, 16, v232
	v_and_b32_e32 v251, 0xffff0000, v232
	v_lshlrev_b32_e32 v252, 16, v233
	v_and_b32_e32 v253, 0xffff0000, v233
	v_mul_f32_e32 v58, v58, v250
	v_mul_f32_e32 v59, v59, v251
	v_mul_f32_e32 v60, v60, v252
	v_mul_f32_e32 v61, v61, v253
	v_cvt_pk_bf16_f32 v230, v62, v63
	v_cvt_pk_bf16_f32 v231, v64, v65
	v_cvt_pk_bf16_f32 v232, v58, v59
	v_cvt_pk_bf16_f32 v233, v60, v61
	global_store_dwordx4 v249, v[230:233], s[14:15]
	s_waitcnt vmcnt(15)
	v_lshlrev_b32_e32 v250, 16, v234
	v_and_b32_e32 v251, 0xffff0000, v234
	v_lshlrev_b32_e32 v252, 16, v235
	v_and_b32_e32 v253, 0xffff0000, v235
	v_mul_f32_e32 v54, v54, v250
	v_mul_f32_e32 v55, v55, v251
	v_mul_f32_e32 v56, v56, v252
	v_mul_f32_e32 v57, v57, v253
	v_lshlrev_b32_e32 v250, 16, v236
	v_and_b32_e32 v251, 0xffff0000, v236
	v_lshlrev_b32_e32 v252, 16, v237
	v_and_b32_e32 v253, 0xffff0000, v237
	v_mul_f32_e32 v50, v50, v250
	v_mul_f32_e32 v51, v51, v251
	v_mul_f32_e32 v52, v52, v252
	v_mul_f32_e32 v53, v53, v253
	v_cvt_pk_bf16_f32 v234, v54, v55
	v_cvt_pk_bf16_f32 v235, v56, v57
	v_cvt_pk_bf16_f32 v236, v50, v51
	v_cvt_pk_bf16_f32 v237, v52, v53
	global_store_dwordx4 v249, v[234:237], s[14:15] offset:256
	v_add_u32_e32 v249, 0x48000, v247
	s_waitcnt vmcnt(15)
	v_lshlrev_b32_e32 v250, 16, v238
	v_and_b32_e32 v251, 0xffff0000, v238
	v_lshlrev_b32_e32 v252, 16, v239
	v_and_b32_e32 v253, 0xffff0000, v239
	v_mul_f32_e32 v46, v46, v250
	v_mul_f32_e32 v47, v47, v251
	v_mul_f32_e32 v48, v48, v252
	v_mul_f32_e32 v49, v49, v253
	v_lshlrev_b32_e32 v250, 16, v240
	v_and_b32_e32 v251, 0xffff0000, v240
	v_lshlrev_b32_e32 v252, 16, v241
	v_and_b32_e32 v253, 0xffff0000, v241
	v_mul_f32_e32 v42, v42, v250
	v_mul_f32_e32 v43, v43, v251
	v_mul_f32_e32 v44, v44, v252
	v_mul_f32_e32 v45, v45, v253
	v_cvt_pk_bf16_f32 v238, v46, v47
	v_cvt_pk_bf16_f32 v239, v48, v49
	v_cvt_pk_bf16_f32 v240, v42, v43
	v_cvt_pk_bf16_f32 v241, v44, v45
	global_store_dwordx4 v249, v[238:241], s[14:15]
	s_waitcnt vmcnt(15)
; __device__ __forceinline__ unsigned cvt_pk_bf16(float lo, float hi) { unsigned r; asm volatile("v_cvt_pk_bf16_f32 %0, %1, %2" : "=v"(r) : "v"(lo), "v"(hi)); return r; }
; __device__ __forceinline__ float bflo(unsigned w) { return __uint_as_float(w << 16); }
; __device__ __forceinline__ float bfhi(unsigned w) { return __uint_as_float(w & 0xffff0000u); }
; #define PG8_BAR __builtin_amdgcn_s_barrier()
; template <class Epi, class Sched>
; __device__ __forceinline__ void gemm_phase(LAS unsigned char* lds, const Gemm g, const Sched& S, const Epi& E, const int tid) {
;     ...
;         if (wr == 0) PG8_BAR;
;         E(acc, cur, wr, wc, fr, fq, lds + STAGE_BYTES + (ui & 1) * 2048);
;         if (!has_next) break;
;         if (!(Epi::CHAIN && nxt.seg != 0))
; #pragma unroll
;         for (int a = 0; a < 2; ++a)
; #pragma unroll
;             for (int b = 0; b < 2; ++b)
; #pragma unroll
;                 for (int m = 0; m < 4; ++m)
; #pragma unroll
;                     for (int n = 0; n < 2; ++n) acc[a][b][m][n] = (f32x4){0.f, 0.f, 0.f, 0.f};
;         cur = nxt; cA = nA; cB = nB; ++ui;
;         E.prep(cur, lds + STAGE_BYTES + (ui & 1) * 2048, tid);
;         if (wr == 1) PG8_BAR;
;     }
;     __device__ __forceinline__ void operator()(f32x4 (&acc)[2][2][4][2], const pg8::Unit& u, int wr, int wc, int fr, int fq, LAS unsigned char*) const {
;     ...
;             for (int m = 0; m < 4; ++m) {
;                 const int row = row0 + ai * 128 + m * 16;
; #pragma unroll
;                 for (int bj = 0; bj < 2; ++bj) {
;                     const int col = col0 + bj * 128;
;                     const u32x4 gw = *(const u32x4*)(gates + (size_t)row * 3072 + 2048 + col);
;                     const f32x4 v0 = acc[ai][bj][m][0], v1 = acc[ai][bj][m][1];
;                     u32x4 w; w.x = cvt_pk_bf16(v0[0] * bflo(gw.x), v0[1] * bfhi(gw.x)); w.y = cvt_pk_bf16(v0[2] * bflo(gw.y), v0[3] * bfhi(gw.y));
;                     w.z = cvt_pk_bf16(v1[0] * bflo(gw.z), v1[1] * bfhi(gw.z)); w.w = cvt_pk_bf16(v1[2] * bflo(gw.w), v1[3] * bfhi(gw.w));
;                     *(u32x4*)(Y + (size_t)row * DM + col) = w;
;                 }
;             }
	v_lshlrev_b32_e32 v250, 16, v130
	v_and_b32_e32 v251, 0xffff0000, v130
	v_lshlrev_b32_e32 v252, 16, v131
	v_and_b32_e32 v253, 0xffff0000, v131
	v_mul_f32_e32 v38, v38, v250
	v_mul_f32_e32 v39, v39, v251
	v_mul_f32_e32 v40, v40, v252
	v_mul_f32_e32 v41, v41, v253
	v_lshlrev_b32_e32 v250, 16, v132
	v_and_b32_e32 v251, 0xffff0000, v132
	v_lshlrev_b32_e32 v252, 16, v133
	v_and_b32_e32 v253, 0xffff0000, v133
	v_mul_f32_e32 v34, v34, v250
	v_mul_f32_e32 v35, v35, v251
	v_mul_f32_e32 v36, v36, v252
	v_mul_f32_e32 v37, v37, v253
	v_cvt_pk_bf16_f32 v130, v38, v39
	v_cvt_pk_bf16_f32 v131, v40, v41
	v_cvt_pk_bf16_f32 v132, v34, v35
	v_cvt_pk_bf16_f32 v133, v36, v37
	global_store_dwordx4 v249, v[130:133], s[14:15] offset:256
	v_add_u32_e32 v249, 0x50000, v247
	s_waitcnt vmcnt(15)
	v_lshlrev_b32_e32 v250, 16, v134
	v_and_b32_e32 v251, 0xffff0000, v134
	v_lshlrev_b32_e32 v252, 16, v135
	v_and_b32_e32 v253, 0xffff0000, v135
	v_mul_f32_e32 v30, v30, v250
	v_mul_f32_e32 v31, v31, v251
	v_mul_f32_e32 v32, v32, v252
	v_mul_f32_e32 v33, v33, v253
	v_lshlrev_b32_e32 v250, 16, v136
	v_and_b32_e32 v251, 0xffff0000, v136
	v_lshlrev_b32_e32 v252, 16, v137
	v_and_b32_e32 v253, 0xffff0000, v137
	v_mul_f32_e32 v26, v26, v250
	v_mul_f32_e32 v27, v27, v251
	v_mul_f32_e32 v28, v28, v252
	v_mul_f32_e32 v29, v29, v253
	v_cvt_pk_bf16_f32 v134, v30, v31
	v_cvt_pk_bf16_f32 v135, v32, v33
	v_cvt_pk_bf16_f32 v136, v26, v27
	v_cvt_pk_bf16_f32 v137, v28, v29
	global_store_dwordx4 v249, v[134:137], s[14:15]
	s_waitcnt vmcnt(15)
	v_lshlrev_b32_e32 v250, 16, v170
	v_and_b32_e32 v251, 0xffff0000, v170
	v_lshlrev_b32_e32 v252, 16, v171
	v_and_b32_e32 v253, 0xffff0000, v171
	v_mul_f32_e32 v22, v22, v250
	v_mul_f32_e32 v23, v23, v251
	v_mul_f32_e32 v24, v24, v252
	v_mul_f32_e32 v25, v25, v253
	v_lshlrev_b32_e32 v250, 16, v172
	v_and_b32_e32 v251, 0xffff0000, v172
	v_lshlrev_b32_e32 v252, 16, v173
	v_and_b32_e32 v253, 0xffff0000, v173
	v_mul_f32_e32 v18, v18, v250
	v_mul_f32_e32 v19, v19, v251
	v_mul_f32_e32 v20, v20, v252
	v_mul_f32_e32 v21, v21, v253
	v_cvt_pk_bf16_f32 v170, v22, v23
	v_cvt_pk_bf16_f32 v171, v24, v25
	v_cvt_pk_bf16_f32 v172, v18, v19
	v_cvt_pk_bf16_f32 v173, v20, v21
	global_store_dwordx4 v249, v[170:173], s[14:15] offset:256
	v_add_u32_e32 v249, 0x58000, v247
	s_waitcnt vmcnt(15)
	v_lshlrev_b32_e32 v250, 16, v174
	v_and_b32_e32 v251, 0xffff0000, v174
	v_lshlrev_b32_e32 v252, 16, v175
	v_and_b32_e32 v253, 0xffff0000, v175
	v_mul_f32_e32 v14, v14, v250
	v_mul_f32_e32 v15, v15, v251
	v_mul_f32_e32 v16, v16, v252
	v_mul_f32_e32 v17, v17, v253
	v_lshlrev_b32_e32 v250, 16, v176
	v_and_b32_e32 v251, 0xffff0000, v176
	v_lshlrev_b32_e32 v252, 16, v177
	v_and_b32_e32 v253, 0xffff0000, v177
	v_mul_f32_e32 v10, v10, v250
	v_mul_f32_e32 v11, v11, v251
	v_mul_f32_e32 v12, v12, v252
	v_mul_f32_e32 v13, v13, v253
	v_cvt_pk_bf16_f32 v174, v14, v15
	v_cvt_pk_bf16_f32 v175, v16, v17
	v_cvt_pk_bf16_f32 v176, v10, v11
	v_cvt_pk_bf16_f32 v177, v12, v13
	global_store_dwordx4 v249, v[174:177], s[14:15]
	s_waitcnt vmcnt(15)
	v_lshlrev_b32_e32 v250, 16, v178
	v_and_b32_e32 v251, 0xffff0000, v178
	v_lshlrev_b32_e32 v252, 16, v179
	v_and_b32_e32 v253, 0xffff0000, v179
	v_mul_f32_e32 v6, v6, v250
	v_mul_f32_e32 v7, v7, v251
	v_mul_f32_e32 v8, v8, v252
	v_mul_f32_e32 v9, v9, v253
	v_lshlrev_b32_e32 v250, 16, v180
	v_and_b32_e32 v251, 0xffff0000, v180
	v_lshlrev_b32_e32 v252, 16, v181
	v_and_b32_e32 v253, 0xffff0000, v181
	v_mul_f32_e32 v2, v2, v250
	v_mul_f32_e32 v3, v3, v251
	v_mul_f32_e32 v4, v4, v252
	v_mul_f32_e32 v5, v5, v253
	v_cvt_pk_bf16_f32 v178, v6, v7
	v_cvt_pk_bf16_f32 v179, v8, v9
	v_cvt_pk_bf16_f32 v180, v2, v3
	v_cvt_pk_bf16_f32 v181, v4, v5
	global_store_dwordx4 v249, v[178:181], s[14:15] offset:256
	s_andn2_b64 vcc, exec, s[4:5]
	s_mov_b64 s[4:5], -1
	s_cbranch_vccnz .LBB0_95
	s_andn2_b64 vcc, exec, s[6:7]
	s_cbranch_vccnz .LBB0_94
	s_barrier
	s_branch .LBB0_94
